# v35 + grid barrier: every workgroup polls the top-level generation word directly (one release hop fewer); leader no longer bumps the per-XCD word
# baseline (speedup 1.0000x reference)
; __device__ __forceinline__ unsigned xb_ld(unsigned* p)              { return __hip_atomic_load(p, __ATOMIC_RELAXED, __HIP_MEMORY_SCOPE_AGENT); }
; __device__ __forceinline__ unsigned xb_add(unsigned* p, unsigned v) { return __hip_atomic_fetch_add(p, v, __ATOMIC_RELAXED, __HIP_MEMORY_SCOPE_AGENT); }
; #define XB_SPIN(cond, bar) do { unsigned _sp = 0; while (cond) { __builtin_amdgcn_s_sleep(1); \
;     if ((++_sp & 255u) == 0u) { if (xb_ld(&(bar)[XB_TMO])) break; if (_sp > XB_SPIN_CAP) { atomicAdd(&(bar)[XB_TMO], 1u); break; } } } } while (0)
; __device__ __forceinline__ void xcd_barrier(const XcdBarrier& b, bool t0) {
;     ...
;         unsigned nloc = b.st[0], nx = b.st[1];
;         if (nloc == 0u) { xcd_barrier_complete(bar, b.x, nloc, nx); b.st[0] = nloc; b.st[1] = nx; }
;         const unsigned old = xb_add(&bar[XB_XSUB(b.x)], 1u);
;         const unsigned gen = old / nloc;
;         if (old + 1u == (gen + 1u) * nloc) {
;             __builtin_amdgcn_fence(__ATOMIC_RELEASE, "agent");
;             asm volatile("s_waitcnt vmcnt(0)" ::: "memory");
;             const unsigned og = xb_add(&bar[XB_TOP], 1u);
;             const unsigned tg = og / nx;
;             if (og + 1u == (tg + 1u) * nx) xb_add(&bar[XB_TOPGEN], 1u);
;             else XB_SPIN(xb_ld(&bar[XB_TOPGEN]) == tg, bar);
;             __builtin_amdgcn_fence(__ATOMIC_ACQUIRE, "agent");
;             xb_add(&bar[XB_XGEN(b.x)], 1u);
;             asm volatile("s_waitcnt vmcnt(0)" ::: "memory");
;         } else {
;             XB_SPIN(xb_ld(&bar[XB_XGEN(b.x)]) == gen, bar);
.LBB0_509:
	s_or_b64 exec, exec, s[36:37]
	v_cvt_f32_u32_e32 v4, v2
	s_waitcnt vmcnt(0)
	v_readfirstlane_b32 s12, v3
	v_sub_u32_e32 v3, 0, v2
	v_rcp_iflag_f32_e32 v4, v4
	v_add_u32_e32 v5, s12, v1
	v_mul_f32_e32 v4, 0x4f7ffffe, v4
	v_cvt_u32_f32_e32 v4, v4
	v_mul_lo_u32 v1, v3, v4
	v_mul_hi_u32 v1, v4, v1
	v_add_u32_e32 v1, v4, v1
	v_mul_hi_u32 v1, v5, v1
	v_mul_lo_u32 v3, v1, v2
	v_sub_u32_e32 v3, v5, v3
	v_add_u32_e32 v4, 1, v1
	v_cmp_ge_u32_e32 vcc, v3, v2
	s_nop 1
	v_cndmask_b32_e32 v1, v1, v4, vcc
	v_sub_u32_e32 v4, v3, v2
	v_cndmask_b32_e32 v3, v3, v4, vcc
	v_add_u32_e32 v4, 1, v1
	v_cmp_ge_u32_e32 vcc, v3, v2
	v_add_u32_e32 v3, 1, v5
	s_nop 0
	v_cndmask_b32_e32 v1, v1, v4, vcc
	v_mul_lo_u32 v4, v2, v1
	v_add_u32_e32 v2, v4, v2
	v_cmp_ne_u32_e32 vcc, v3, v2
	s_and_saveexec_b64 s[14:15], vcc
	s_xor_b64 s[36:37], exec, s[14:15]
	s_cbranch_execz .LBB0_523
	v_readlane_b32 s6, v253, 49
	v_readlane_b32 s7, v253, 50
	s_waitcnt lgkmcnt(0)
	s_nop 3
	global_load_dword v0, v185, s[6:7] sc1
	s_waitcnt vmcnt(0)
	v_cmp_eq_u32_e32 vcc, v0, v1
	s_and_saveexec_b64 s[38:39], vcc
	s_cbranch_execz .LBB0_522
	s_mov_b32 s12, 1
	s_mov_b64 s[40:41], 0
	s_branch .LBB0_513

; __device__ __forceinline__ unsigned xb_ld(unsigned* p)              { return __hip_atomic_load(p, __ATOMIC_RELAXED, __HIP_MEMORY_SCOPE_AGENT); }
; #define XB_SPIN(cond, bar) do { unsigned _sp = 0; while (cond) { __builtin_amdgcn_s_sleep(1); \
;     if ((++_sp & 255u) == 0u) { if (xb_ld(&(bar)[XB_TMO])) break; if (_sp > XB_SPIN_CAP) { atomicAdd(&(bar)[XB_TMO], 1u); break; } } } } while (0)
; __device__ __forceinline__ void xcd_barrier(const XcdBarrier& b, bool t0) {
;     ...
;             XB_SPIN(xb_ld(&bar[XB_XGEN(b.x)]) == gen, bar);
;             __builtin_amdgcn_fence(__ATOMIC_ACQUIRE, "agent");
.LBB0_515:
	v_readlane_b32 s6, v253, 49
	v_readlane_b32 s7, v253, 50
	s_add_i32 s12, s12, 1
	s_mov_b64 s[46:47], -1
	s_nop 2
	global_load_dword v0, v185, s[6:7] sc1
	s_waitcnt vmcnt(0)
	v_cmp_ne_u32_e32 vcc, v0, v1
	s_orn2_b64 s[44:45], vcc, exec
	s_branch .LBB0_512

; __device__ __forceinline__ unsigned xb_add(unsigned* p, unsigned v) { return __hip_atomic_fetch_add(p, v, __ATOMIC_RELAXED, __HIP_MEMORY_SCOPE_AGENT); }
; __device__ __forceinline__ void xcd_barrier(const XcdBarrier& b, bool t0) {
;     ...
;             __builtin_amdgcn_fence(__ATOMIC_ACQUIRE, "agent");
;             xb_add(&bar[XB_XGEN(b.x)], 1u);
;             asm volatile("s_waitcnt vmcnt(0)" ::: "memory");
.LBB0_540:
	s_or_b64 exec, exec, s[36:37]
	s_mov_b64 s[36:37], exec
	v_mbcnt_lo_u32_b32 v0, s36, 0
	v_mbcnt_hi_u32_b32 v0, s37, v0
	v_cmp_eq_u32_e32 vcc, 0, v0
	s_waitcnt vmcnt(0)
	buffer_inv sc1
	s_and_saveexec_b64 s[38:39], vcc
	s_cbranch_execz .LBB0_542
	s_bcnt1_i32_b64 s12, s[36:37]
	v_readlane_b32 s6, v253, 45
	v_mov_b32_e32 v0, s12
	v_readlane_b32 s7, v253, 46
	s_nop 4
.LBB0_542:
	s_or_b64 exec, exec, s[38:39]
	s_waitcnt vmcnt(0)

; __device__ __forceinline__ unsigned xb_ld(unsigned* p)              { return __hip_atomic_load(p, __ATOMIC_RELAXED, __HIP_MEMORY_SCOPE_AGENT); }
; __device__ __forceinline__ unsigned xb_add(unsigned* p, unsigned v) { return __hip_atomic_fetch_add(p, v, __ATOMIC_RELAXED, __HIP_MEMORY_SCOPE_AGENT); }
; #define XB_SPIN(cond, bar) do { unsigned _sp = 0; while (cond) { __builtin_amdgcn_s_sleep(1); \
;     if ((++_sp & 255u) == 0u) { if (xb_ld(&(bar)[XB_TMO])) break; if (_sp > XB_SPIN_CAP) { atomicAdd(&(bar)[XB_TMO], 1u); break; } } } } while (0)
; __device__ __forceinline__ void xcd_barrier(const XcdBarrier& b, bool t0) {
;     ...
;         unsigned nloc = b.st[0], nx = b.st[1];
;         if (nloc == 0u) { xcd_barrier_complete(bar, b.x, nloc, nx); b.st[0] = nloc; b.st[1] = nx; }
;         const unsigned old = xb_add(&bar[XB_XSUB(b.x)], 1u);
;         const unsigned gen = old / nloc;
;         if (old + 1u == (gen + 1u) * nloc) {
;             __builtin_amdgcn_fence(__ATOMIC_RELEASE, "agent");
;             asm volatile("s_waitcnt vmcnt(0)" ::: "memory");
;             const unsigned og = xb_add(&bar[XB_TOP], 1u);
;             const unsigned tg = og / nx;
;             if (og + 1u == (tg + 1u) * nx) xb_add(&bar[XB_TOPGEN], 1u);
;             else XB_SPIN(xb_ld(&bar[XB_TOPGEN]) == tg, bar);
;             __builtin_amdgcn_fence(__ATOMIC_ACQUIRE, "agent");
;             xb_add(&bar[XB_XGEN(b.x)], 1u);
;             asm volatile("s_waitcnt vmcnt(0)" ::: "memory");
;         } else {
;             XB_SPIN(xb_ld(&bar[XB_XGEN(b.x)]) == gen, bar);
.LBB0_627:
	s_or_b64 exec, exec, s[36:37]
	v_cvt_f32_u32_e32 v4, v2
	s_waitcnt vmcnt(0)
	v_readfirstlane_b32 s6, v3
	v_sub_u32_e32 v3, 0, v2
	v_rcp_iflag_f32_e32 v4, v4
	v_add_u32_e32 v5, s6, v1
	v_mul_f32_e32 v4, 0x4f7ffffe, v4
	v_cvt_u32_f32_e32 v4, v4
	v_mul_lo_u32 v1, v3, v4
	v_mul_hi_u32 v1, v4, v1
	v_add_u32_e32 v1, v4, v1
	v_mul_hi_u32 v1, v5, v1
	v_mul_lo_u32 v3, v1, v2
	v_sub_u32_e32 v3, v5, v3
	v_add_u32_e32 v4, 1, v1
	v_cmp_ge_u32_e32 vcc, v3, v2
	s_nop 1
	v_cndmask_b32_e32 v1, v1, v4, vcc
	v_sub_u32_e32 v4, v3, v2
	v_cndmask_b32_e32 v3, v3, v4, vcc
	v_add_u32_e32 v4, 1, v1
	v_cmp_ge_u32_e32 vcc, v3, v2
	v_add_u32_e32 v3, 1, v5
	s_nop 0
	v_cndmask_b32_e32 v1, v1, v4, vcc
	v_mul_lo_u32 v4, v2, v1
	v_add_u32_e32 v2, v4, v2
	v_cmp_ne_u32_e32 vcc, v3, v2
	s_and_saveexec_b64 s[14:15], vcc
	s_xor_b64 s[36:37], exec, s[14:15]
	s_cbranch_execz .LBB0_641
	v_readlane_b32 s6, v253, 49
	v_readlane_b32 s7, v253, 50
	s_waitcnt lgkmcnt(0)
	s_nop 3
	global_load_dword v0, v185, s[6:7] sc1
	s_waitcnt vmcnt(0)
	v_cmp_eq_u32_e32 vcc, v0, v1
	s_and_saveexec_b64 s[38:39], vcc
	s_cbranch_execz .LBB0_640
	s_mov_b32 s12, 1
	s_mov_b64 s[40:41], 0
	s_branch .LBB0_631

; __device__ __forceinline__ unsigned xb_add(unsigned* p, unsigned v) { return __hip_atomic_fetch_add(p, v, __ATOMIC_RELAXED, __HIP_MEMORY_SCOPE_AGENT); }
; __device__ __forceinline__ void xcd_barrier(const XcdBarrier& b, bool t0) {
;     ...
;             __builtin_amdgcn_fence(__ATOMIC_ACQUIRE, "agent");
;             xb_add(&bar[XB_XGEN(b.x)], 1u);
;             asm volatile("s_waitcnt vmcnt(0)" ::: "memory");
.LBB0_658:
	s_or_b64 exec, exec, s[36:37]
	s_mov_b64 s[36:37], exec
	v_mbcnt_lo_u32_b32 v0, s36, 0
	v_mbcnt_hi_u32_b32 v0, s37, v0
	v_cmp_eq_u32_e32 vcc, 0, v0
	s_waitcnt vmcnt(0)
	buffer_inv sc1
	s_and_saveexec_b64 s[38:39], vcc
	s_cbranch_execz .LBB0_660
	s_bcnt1_i32_b64 s6, s[36:37]
	v_mov_b32_e32 v0, s6
	v_readlane_b32 s6, v253, 45
	v_readlane_b32 s7, v253, 46
	s_nop 4
.LBB0_660:
	s_or_b64 exec, exec, s[38:39]
	s_waitcnt vmcnt(0)

; __device__ __forceinline__ unsigned xb_add(unsigned* p, unsigned v) { return __hip_atomic_fetch_add(p, v, __ATOMIC_RELAXED, __HIP_MEMORY_SCOPE_AGENT); }
; __device__ __forceinline__ void xcd_barrier(const XcdBarrier& b, bool t0) {
;     ...
;             __builtin_amdgcn_fence(__ATOMIC_ACQUIRE, "agent");
;             xb_add(&bar[XB_XGEN(b.x)], 1u);
;             asm volatile("s_waitcnt vmcnt(0)" ::: "memory");
.LBB0_732:
	s_or_b64 exec, exec, s[36:37]
	s_mov_b64 s[36:37], exec
	v_mbcnt_lo_u32_b32 v0, s36, 0
	v_mbcnt_hi_u32_b32 v0, s37, v0
	v_cmp_eq_u32_e32 vcc, 0, v0
	s_waitcnt vmcnt(0)
	buffer_inv sc1
	s_and_saveexec_b64 s[38:39], vcc
	s_cbranch_execz .LBB0_734
	s_bcnt1_i32_b64 s6, s[36:37]
	v_mov_b32_e32 v0, s6
	v_readlane_b32 s6, v253, 45
	v_readlane_b32 s7, v253, 46
	s_nop 4
.LBB0_734:
	s_or_b64 exec, exec, s[38:39]
	s_waitcnt vmcnt(0)

; __device__ __forceinline__ unsigned xb_add(unsigned* p, unsigned v) { return __hip_atomic_fetch_add(p, v, __ATOMIC_RELAXED, __HIP_MEMORY_SCOPE_AGENT); }
; __device__ __forceinline__ void xcd_barrier(const XcdBarrier& b, bool t0) {
;     ...
;             __builtin_amdgcn_fence(__ATOMIC_ACQUIRE, "agent");
;             xb_add(&bar[XB_XGEN(b.x)], 1u);
;             asm volatile("s_waitcnt vmcnt(0)" ::: "memory");
.LBB0_890:
	s_or_b64 exec, exec, s[36:37]
	s_mov_b64 s[36:37], exec
	v_mbcnt_lo_u32_b32 v0, s36, 0
	v_mbcnt_hi_u32_b32 v0, s37, v0
	v_cmp_eq_u32_e32 vcc, 0, v0
	s_waitcnt vmcnt(0)
	buffer_inv sc1
	s_and_saveexec_b64 s[38:39], vcc
	s_cbranch_execz .LBB0_892
	s_bcnt1_i32_b64 s6, s[36:37]
	v_mov_b32_e32 v0, s6
	v_readlane_b32 s6, v253, 45
	v_readlane_b32 s7, v253, 46
	s_nop 4
.LBB0_892:
	s_or_b64 exec, exec, s[38:39]
	s_waitcnt vmcnt(0)

; __device__ __forceinline__ unsigned xb_add(unsigned* p, unsigned v) { return __hip_atomic_fetch_add(p, v, __ATOMIC_RELAXED, __HIP_MEMORY_SCOPE_AGENT); }
; __device__ __forceinline__ void xcd_barrier(const XcdBarrier& b, bool t0) {
;     ...
;             __builtin_amdgcn_fence(__ATOMIC_ACQUIRE, "agent");
;             xb_add(&bar[XB_XGEN(b.x)], 1u);
;             asm volatile("s_waitcnt vmcnt(0)" ::: "memory");
.LBB0_997:
	s_or_b64 exec, exec, s[36:37]
	s_mov_b64 s[36:37], exec
	v_mbcnt_lo_u32_b32 v0, s36, 0
	v_mbcnt_hi_u32_b32 v0, s37, v0
	v_cmp_eq_u32_e32 vcc, 0, v0
	s_waitcnt vmcnt(0)
	buffer_inv sc1
	s_and_saveexec_b64 s[38:39], vcc
	s_cbranch_execz .LBB0_999
	s_bcnt1_i32_b64 s6, s[36:37]
	v_mov_b32_e32 v0, s6
	v_readlane_b32 s6, v253, 45
	v_readlane_b32 s7, v253, 46
	s_nop 4
.LBB0_999:
	s_or_b64 exec, exec, s[38:39]
	s_waitcnt vmcnt(0)

; __device__ __forceinline__ unsigned xb_ld(unsigned* p)              { return __hip_atomic_load(p, __ATOMIC_RELAXED, __HIP_MEMORY_SCOPE_AGENT); }
; __device__ __forceinline__ unsigned xb_add(unsigned* p, unsigned v) { return __hip_atomic_fetch_add(p, v, __ATOMIC_RELAXED, __HIP_MEMORY_SCOPE_AGENT); }
; #define XB_SPIN(cond, bar) do { unsigned _sp = 0; while (cond) { __builtin_amdgcn_s_sleep(1); \
;     if ((++_sp & 255u) == 0u) { if (xb_ld(&(bar)[XB_TMO])) break; if (_sp > XB_SPIN_CAP) { atomicAdd(&(bar)[XB_TMO], 1u); break; } } } } while (0)
; __device__ __forceinline__ void xcd_barrier(const XcdBarrier& b, bool t0) {
;     ...
;         unsigned nloc = b.st[0], nx = b.st[1];
;         if (nloc == 0u) { xcd_barrier_complete(bar, b.x, nloc, nx); b.st[0] = nloc; b.st[1] = nx; }
;         const unsigned old = xb_add(&bar[XB_XSUB(b.x)], 1u);
;         const unsigned gen = old / nloc;
;         if (old + 1u == (gen + 1u) * nloc) {
;             __builtin_amdgcn_fence(__ATOMIC_RELEASE, "agent");
;             asm volatile("s_waitcnt vmcnt(0)" ::: "memory");
;             const unsigned og = xb_add(&bar[XB_TOP], 1u);
;             const unsigned tg = og / nx;
;             if (og + 1u == (tg + 1u) * nx) xb_add(&bar[XB_TOPGEN], 1u);
;             else XB_SPIN(xb_ld(&bar[XB_TOPGEN]) == tg, bar);
;             __builtin_amdgcn_fence(__ATOMIC_ACQUIRE, "agent");
;             xb_add(&bar[XB_XGEN(b.x)], 1u);
;             asm volatile("s_waitcnt vmcnt(0)" ::: "memory");
;         } else {
;             XB_SPIN(xb_ld(&bar[XB_XGEN(b.x)]) == gen, bar);
.LBB0_1049:
	s_or_b64 exec, exec, s[38:39]
	v_cvt_f32_u32_e32 v4, v2
	s_waitcnt vmcnt(0)
	v_readfirstlane_b32 s6, v3
	v_sub_u32_e32 v3, 0, v2
	v_rcp_iflag_f32_e32 v4, v4
	v_add_u32_e32 v5, s6, v1
	v_mul_f32_e32 v4, 0x4f7ffffe, v4
	v_cvt_u32_f32_e32 v4, v4
	v_mul_lo_u32 v1, v3, v4
	v_mul_hi_u32 v1, v4, v1
	v_add_u32_e32 v1, v4, v1
	v_mul_hi_u32 v1, v5, v1
	v_mul_lo_u32 v3, v1, v2
	v_sub_u32_e32 v3, v5, v3
	v_add_u32_e32 v4, 1, v1
	v_cmp_ge_u32_e32 vcc, v3, v2
	s_nop 1
	v_cndmask_b32_e32 v1, v1, v4, vcc
	v_sub_u32_e32 v4, v3, v2
	v_cndmask_b32_e32 v3, v3, v4, vcc
	v_add_u32_e32 v4, 1, v1
	v_cmp_ge_u32_e32 vcc, v3, v2
	v_add_u32_e32 v3, 1, v5
	s_nop 0
	v_cndmask_b32_e32 v1, v1, v4, vcc
	v_mul_lo_u32 v4, v2, v1
	v_add_u32_e32 v2, v4, v2
	v_cmp_ne_u32_e32 vcc, v3, v2
	s_and_saveexec_b64 s[14:15], vcc
	s_xor_b64 s[38:39], exec, s[14:15]
	s_cbranch_execz .LBB0_1063
	v_readlane_b32 s6, v253, 49
	v_readlane_b32 s7, v253, 50
	s_waitcnt lgkmcnt(0)
	s_nop 3
	global_load_dword v0, v185, s[6:7] sc1
	s_waitcnt vmcnt(0)
	v_cmp_eq_u32_e32 vcc, v0, v1
	s_and_saveexec_b64 s[40:41], vcc
	s_cbranch_execz .LBB0_1062
	s_mov_b32 s12, 1
	s_mov_b64 s[42:43], 0
	s_branch .LBB0_1053

; __device__ __forceinline__ unsigned xb_ld(unsigned* p)              { return __hip_atomic_load(p, __ATOMIC_RELAXED, __HIP_MEMORY_SCOPE_AGENT); }
; #define XB_SPIN(cond, bar) do { unsigned _sp = 0; while (cond) { __builtin_amdgcn_s_sleep(1); \
;     if ((++_sp & 255u) == 0u) { if (xb_ld(&(bar)[XB_TMO])) break; if (_sp > XB_SPIN_CAP) { atomicAdd(&(bar)[XB_TMO], 1u); break; } } } } while (0)
; __device__ __forceinline__ void xcd_barrier(const XcdBarrier& b, bool t0) {
;     ...
;             XB_SPIN(xb_ld(&bar[XB_XGEN(b.x)]) == gen, bar);
;             __builtin_amdgcn_fence(__ATOMIC_ACQUIRE, "agent");
.LBB0_1055:
	v_readlane_b32 s6, v253, 49
	v_readlane_b32 s7, v253, 50
	s_add_i32 s12, s12, 1
	s_mov_b64 s[50:51], -1
	s_nop 2
	global_load_dword v0, v185, s[6:7] sc1
	s_waitcnt vmcnt(0)
	v_cmp_ne_u32_e32 vcc, v0, v1
	s_orn2_b64 s[46:47], vcc, exec
	s_branch .LBB0_1052

; __device__ __forceinline__ unsigned xb_add(unsigned* p, unsigned v) { return __hip_atomic_fetch_add(p, v, __ATOMIC_RELAXED, __HIP_MEMORY_SCOPE_AGENT); }
; __device__ __forceinline__ void xcd_barrier(const XcdBarrier& b, bool t0) {
;     ...
;             __builtin_amdgcn_fence(__ATOMIC_ACQUIRE, "agent");
;             xb_add(&bar[XB_XGEN(b.x)], 1u);
;             asm volatile("s_waitcnt vmcnt(0)" ::: "memory");
.LBB0_1080:
	s_or_b64 exec, exec, s[38:39]
	s_mov_b64 s[38:39], exec
	v_mbcnt_lo_u32_b32 v0, s38, 0
	v_mbcnt_hi_u32_b32 v0, s39, v0
	v_cmp_eq_u32_e32 vcc, 0, v0
	s_waitcnt vmcnt(0)
	buffer_inv sc1
	s_and_saveexec_b64 s[40:41], vcc
	s_cbranch_execz .LBB0_1082
	s_bcnt1_i32_b64 s6, s[38:39]
	v_mov_b32_e32 v0, s6
	v_readlane_b32 s6, v253, 45
	v_readlane_b32 s7, v253, 46
	s_nop 4
.LBB0_1082:
	s_or_b64 exec, exec, s[40:41]
	s_waitcnt vmcnt(0)

; __device__ __forceinline__ unsigned xb_add(unsigned* p, unsigned v) { return __hip_atomic_fetch_add(p, v, __ATOMIC_RELAXED, __HIP_MEMORY_SCOPE_AGENT); }
; __device__ __forceinline__ void xcd_barrier(const XcdBarrier& b, bool t0) {
;     ...
;             __builtin_amdgcn_fence(__ATOMIC_ACQUIRE, "agent");
;             xb_add(&bar[XB_XGEN(b.x)], 1u);
;             asm volatile("s_waitcnt vmcnt(0)" ::: "memory");
.LBB0_1213:
	s_or_b64 exec, exec, s[38:39]
	s_mov_b64 s[38:39], exec
	v_mbcnt_lo_u32_b32 v0, s38, 0
	v_mbcnt_hi_u32_b32 v0, s39, v0
	v_cmp_eq_u32_e32 vcc, 0, v0
	s_waitcnt vmcnt(0)
	buffer_inv sc1
	s_and_saveexec_b64 s[40:41], vcc
	s_cbranch_execz .LBB0_1215
	s_bcnt1_i32_b64 s6, s[38:39]
	v_mov_b32_e32 v0, s6
	v_readlane_b32 s6, v253, 45
	v_readlane_b32 s7, v253, 46
	s_nop 4
.LBB0_1215:
	s_or_b64 exec, exec, s[40:41]
	s_waitcnt vmcnt(0)

; __device__ __forceinline__ unsigned xb_add(unsigned* p, unsigned v) { return __hip_atomic_fetch_add(p, v, __ATOMIC_RELAXED, __HIP_MEMORY_SCOPE_AGENT); }
; __device__ __forceinline__ void xcd_barrier(const XcdBarrier& b, bool t0) {
;     ...
;             __builtin_amdgcn_fence(__ATOMIC_ACQUIRE, "agent");
;             xb_add(&bar[XB_XGEN(b.x)], 1u);
;             asm volatile("s_waitcnt vmcnt(0)" ::: "memory");
.LBB0_1296:
	s_or_b64 exec, exec, s[38:39]
	s_mov_b64 s[38:39], exec
	v_mbcnt_lo_u32_b32 v0, s38, 0
	v_mbcnt_hi_u32_b32 v0, s39, v0
	v_cmp_eq_u32_e32 vcc, 0, v0
	s_waitcnt vmcnt(0)
	buffer_inv sc1
	s_and_saveexec_b64 s[40:41], vcc
	s_cbranch_execz .LBB0_1298
	s_bcnt1_i32_b64 s6, s[38:39]
	v_mov_b32_e32 v0, s6
	v_readlane_b32 s6, v253, 45
	v_readlane_b32 s7, v253, 46
	s_nop 4
.LBB0_1298:
	s_or_b64 exec, exec, s[40:41]
	s_waitcnt vmcnt(0)

; __device__ __forceinline__ unsigned xb_add(unsigned* p, unsigned v) { return __hip_atomic_fetch_add(p, v, __ATOMIC_RELAXED, __HIP_MEMORY_SCOPE_AGENT); }
; __device__ __forceinline__ void xcd_barrier(const XcdBarrier& b, bool t0) {
;     ...
;             __builtin_amdgcn_fence(__ATOMIC_ACQUIRE, "agent");
;             xb_add(&bar[XB_XGEN(b.x)], 1u);
;             asm volatile("s_waitcnt vmcnt(0)" ::: "memory");
.LBB0_1406:
	s_bcnt1_i32_b64 s6, s[36:37]
	v_mov_b32_e32 v0, s6
	v_readlane_b32 s6, v253, 45
	v_readlane_b32 s7, v253, 46
	s_nop 4
	s_getpc_b64 s[98:99]
